# layer-0 f32-residual epilogue: residual loads coalesced by lane transpose (32-B chunks) + bpermute back
# speedup vs baseline: 1.0144x; 1.0144x over previous
;     __device__ __forceinline__ void operator()(const f32x4 (&acc)[2][2][4][2], const Unit& u, int wr, int wc, int fr, int fq) const {
;     ...
;         if (res32) {
; #pragma unroll
;             for (int ai = 0; ai < 2; ++ai) { f32x4 r[4][2][2];
; #pragma unroll
;                 for (int m = 0; m < 4; ++m)
; #pragma unroll
;                     for (int bj = 0; bj < 2; ++bj) { const size_t off = (size_t)(u.pm * BM + rl0 + ai * HALF + m * 16) * 1024 + col0 + bj * HALF;
;                         r[m][bj][0] = *(const f32x4*)(res32 + off); r[m][bj][1] = *(const f32x4*)(res32 + off + 4); }
.LBB0_362:
	s_lshl_b32 s51, s80, 8
	v_mov_b32_e32 v130, v195
	v_mov_b32_e32 v217, v193
	s_or_b32 s51, s51, s37
	s_andn2_b64 vcc, exec, s[46:47]
	v_add_u32_e32 v216, s36, v130
	v_lshl_add_u32 v206, v217, 3, s51
	s_lshl_b32 s51, s70, 8
	v_add_u32_e32 v208, s51, v216
	v_ashrrev_i32_e32 v207, 31, v206
	v_cmp_eq_u32_e64 s[58:59], 0, v217
	v_ashrrev_i32_e32 v209, 31, v208
	s_cbranch_vccnz .LBB0_380
	v_mbcnt_lo_u32_b32 v246, -1, 0
	v_mbcnt_hi_u32_b32 v246, -1, v246
	v_and_b32_e32 v249, 3, v246
	v_lshrrev_b32_e32 v245, 4, v246
	v_sub_u32_e32 v245, v249, v245
	v_lshlrev_b32_e32 v245, 5, v245
	v_and_b32_e32 v244, 15, v246
	v_lshrrev_b32_e32 v249, 2, v246
	v_sub_u32_e32 v249, v249, v244
	v_lshl_add_u32 v244, v244, 2, 0
	v_lshrrev_b32_e32 v246, 4, v246
	v_add_u32_e32 v246, v244, v246
	v_lshlrev_b32_e32 v246, 2, v246
	v_lshl_add_u32 v244, v249, 12, v245
	v_ashrrev_i32_e32 v245, 31, v244
	v_lshl_add_u64 v[178:179], v[206:207], 2, s[28:29]
	v_lshlrev_b64 v[130:131], 12, v[208:209]
	v_lshl_add_u64 v[138:139], v[178:179], 0, v[130:131]
	v_lshl_add_u64 v[250:251], v[138:139], 0, v[244:245]
	global_load_dwordx4 v[180:183], v[250:251], off
	v_lshl_add_u64 v[250:251], v[138:139], 0, v[244:245]
	global_load_dwordx4 v[210:213], v[250:251], off offset:16
	v_lshl_add_u64 v[250:251], v[138:139], 0, v[244:245]
	global_load_dwordx4 v[218:221], v[250:251], off offset:512
	v_lshl_add_u64 v[250:251], v[138:139], 0, v[244:245]
	global_load_dwordx4 v[222:225], v[250:251], off offset:528
	s_mov_b64 s[60:61], 0x10000
	v_lshl_add_u64 v[140:141], v[138:139], 0, s[60:61]
	v_add_co_u32_e32 v142, vcc, 0x10000, v138
	s_mov_b64 s[60:61], 0x20000
	v_lshl_add_u64 v[144:145], v[138:139], 0, s[60:61]
	s_mov_b64 s[60:61], 0x30000
	v_addc_co_u32_e32 v143, vcc, 0, v139, vcc
	s_mov_b32 s53, 0x20000
	v_lshl_add_u64 v[184:185], v[138:139], 0, s[60:61]
	v_lshl_add_u64 v[250:251], v[140:141], 0, v[244:245]
	global_load_dwordx4 v[170:173], v[250:251], off offset:16
	v_lshl_add_u64 v[250:251], v[140:141], 0, v[244:245]
	global_load_dwordx4 v[162:165], v[250:251], off offset:512
	v_add_co_u32_e32 v154, vcc, s53, v138
	v_lshl_add_u64 v[250:251], v[144:145], 0, v[244:245]
	global_load_dwordx4 v[150:153], v[250:251], off offset:16
	v_lshl_add_u64 v[250:251], v[144:145], 0, v[244:245]
	global_load_dwordx4 v[146:149], v[250:251], off offset:512
	v_lshl_add_u64 v[250:251], v[184:185], 0, v[244:245]
	global_load_dwordx4 v[134:137], v[250:251], off offset:16
	v_lshl_add_u64 v[250:251], v[184:185], 0, v[244:245]
	global_load_dwordx4 v[130:133], v[250:251], off offset:512
	v_lshl_add_u64 v[250:251], v[142:143], 0, v[244:245]
	global_load_dwordx4 v[174:177], v[250:251], off
	v_lshl_add_u64 v[250:251], v[140:141], 0, v[244:245]
	global_load_dwordx4 v[166:169], v[250:251], off offset:528
	v_addc_co_u32_e32 v155, vcc, 0, v139, vcc
	s_mov_b32 s53, 0x30000
	v_add_co_u32_e32 v138, vcc, s53, v138
	v_lshl_add_u64 v[250:251], v[154:155], 0, v[244:245]
	global_load_dwordx4 v[158:161], v[250:251], off
	s_nop 0
	v_lshl_add_u64 v[250:251], v[144:145], 0, v[244:245]
	global_load_dwordx4 v[154:157], v[250:251], off offset:528
	v_addc_co_u32_e32 v139, vcc, 0, v139, vcc
	v_lshl_add_u64 v[250:251], v[138:139], 0, v[244:245]
	global_load_dwordx4 v[142:145], v[250:251], off
	s_nop 0
	v_lshl_add_u64 v[250:251], v[184:185], 0, v[244:245]
	global_load_dwordx4 v[138:141], v[250:251], off offset:528
	v_lshlrev_b64 v[184:185], 11, v[208:209]
	v_lshl_add_u64 v[184:185], s[40:41], 0, v[184:185]
	s_lshl_b32 s60, s80, 2
	s_ashr_i32 s61, s60, 31
	s_waitcnt vmcnt(0)
; __device__ __forceinline__ unsigned cvt_pk_bf16(float lo, float hi) { unsigned r; asm volatile("v_cvt_pk_bf16_f32 %0, %1, %2" : "=v"(r) : "v"(lo), "v"(hi)); return r; }
;     __device__ __forceinline__ void finish_half(const f32x4 (&acc)[2][2][4][2], const f32x4 (&r)[4][2][2], const Unit& u, int ai, int rl0, int col0, int wc, int fq) const {
;     ...
;         for (int m = 0; m < 4; ++m) { const size_t row = (size_t)(u.pm * BM + rl0 + ai * HALF + m * 16); const size_t off = row * 1024 + col0; float q = 0.f;
; #pragma unroll
;             for (int bj = 0; bj < 2; ++bj) {
;                 const f32x4 v0 = acc[ai][bj][m][0] + r[m][bj][0], v1 = acc[ai][bj][m][1] + r[m][bj][1];
;                 if (out32) { *(f32x4*)(out32 + off + bj * HALF) = v0; *(f32x4*)(out32 + off + bj * HALF + 4) = v1; }
;                 q += (v0[0] * v0[0] + v0[1] * v0[1]) + (v0[2] * v0[2] + v0[3] * v0[3]) + (v1[0] * v1[0] + v1[1] * v1[1]) + (v1[2] * v1[2] + v1[3] * v1[3]);
;                 u32x4 w; w.x = cvt_pk_bf16(v0[0], v0[1]); w.y = cvt_pk_bf16(v0[2], v0[3]); w.z = cvt_pk_bf16(v1[0], v1[1]); w.w = cvt_pk_bf16(v1[2], v1[3]);
;                 *(u32x4*)(hb + off + bj * HALF) = w; }
;             q += __shfl_xor(q, 16); q += __shfl_xor(q, 32);
;             if (fq == 0) ssq[row * 16 + u.pn * 4 + wc] = q; }
;     __device__ __forceinline__ void operator()(const f32x4 (&acc)[2][2][4][2], const Unit& u, int wr, int wc, int fr, int fq) const {
;     ...
;                     for (int bj = 0; bj < 2; ++bj) { const size_t off = (size_t)(u.pm * BM + rl0 + ai * HALF + m * 16) * 1024 + col0 + bj * HALF;
;                         r[m][bj][0] = *(const f32x4*)(res32 + off); r[m][bj][1] = *(const f32x4*)(res32 + off + 4); }
	ds_bpermute_b32 v180, v246, v180
	ds_bpermute_b32 v181, v246, v181
	ds_bpermute_b32 v182, v246, v182
	ds_bpermute_b32 v183, v246, v183
	ds_bpermute_b32 v210, v246, v210
	ds_bpermute_b32 v211, v246, v211
	ds_bpermute_b32 v212, v246, v212
	ds_bpermute_b32 v213, v246, v213
	ds_bpermute_b32 v218, v246, v218
	ds_bpermute_b32 v219, v246, v219
	ds_bpermute_b32 v220, v246, v220
	ds_bpermute_b32 v221, v246, v221
	ds_bpermute_b32 v222, v246, v222
	ds_bpermute_b32 v223, v246, v223
	ds_bpermute_b32 v224, v246, v224
	ds_bpermute_b32 v225, v246, v225
	ds_bpermute_b32 v170, v246, v170
	ds_bpermute_b32 v171, v246, v171
	ds_bpermute_b32 v172, v246, v172
	ds_bpermute_b32 v173, v246, v173
	ds_bpermute_b32 v162, v246, v162
	ds_bpermute_b32 v163, v246, v163
	ds_bpermute_b32 v164, v246, v164
	ds_bpermute_b32 v165, v246, v165
	ds_bpermute_b32 v150, v246, v150
	ds_bpermute_b32 v151, v246, v151
	ds_bpermute_b32 v152, v246, v152
	ds_bpermute_b32 v153, v246, v153
	ds_bpermute_b32 v146, v246, v146
	ds_bpermute_b32 v147, v246, v147
	ds_bpermute_b32 v148, v246, v148
	ds_bpermute_b32 v149, v246, v149
	ds_bpermute_b32 v134, v246, v134
	ds_bpermute_b32 v135, v246, v135
	ds_bpermute_b32 v136, v246, v136
	ds_bpermute_b32 v137, v246, v137
	ds_bpermute_b32 v130, v246, v130
	ds_bpermute_b32 v131, v246, v131
	ds_bpermute_b32 v132, v246, v132
	ds_bpermute_b32 v133, v246, v133
	ds_bpermute_b32 v174, v246, v174
	ds_bpermute_b32 v175, v246, v175
	ds_bpermute_b32 v176, v246, v176
	ds_bpermute_b32 v177, v246, v177
	ds_bpermute_b32 v166, v246, v166
	ds_bpermute_b32 v167, v246, v167
	ds_bpermute_b32 v168, v246, v168
	ds_bpermute_b32 v169, v246, v169
	ds_bpermute_b32 v158, v246, v158
	ds_bpermute_b32 v159, v246, v159
	ds_bpermute_b32 v160, v246, v160
	ds_bpermute_b32 v161, v246, v161
	ds_bpermute_b32 v154, v246, v154
	ds_bpermute_b32 v155, v246, v155
	ds_bpermute_b32 v156, v246, v156
	ds_bpermute_b32 v157, v246, v157
	ds_bpermute_b32 v142, v246, v142
	ds_bpermute_b32 v143, v246, v143
	ds_bpermute_b32 v144, v246, v144
	ds_bpermute_b32 v145, v246, v145
	ds_bpermute_b32 v138, v246, v138
	ds_bpermute_b32 v139, v246, v139
	ds_bpermute_b32 v140, v246, v140
	ds_bpermute_b32 v141, v246, v141
	s_waitcnt lgkmcnt(0)
	v_pk_add_f32 v[226:227], v[128:129], v[182:183]
	v_pk_add_f32 v[228:229], v[126:127], v[180:181]
	v_pk_add_f32 v[212:213], v[124:125], v[212:213]
	v_pk_add_f32 v[210:211], v[122:123], v[210:211]
	v_pk_add_f32 v[220:221], v[120:121], v[220:221]
	v_pk_add_f32 v[218:219], v[118:119], v[218:219]
	v_pk_add_f32 v[222:223], v[114:115], v[222:223]
	v_mul_f32_e32 v236, v229, v229
	v_mul_f32_e32 v237, v227, v227
	v_mul_f32_e32 v238, v211, v211
	v_mul_f32_e32 v239, v213, v213
	v_cvt_pk_bf16_f32 v180, v228, v229
	v_cvt_pk_bf16_f32 v181, v226, v227
	v_cvt_pk_bf16_f32 v182, v210, v211
	v_cvt_pk_bf16_f32 v183, v212, v213
	v_mul_f32_e32 v211, v219, v219
	v_mul_f32_e32 v213, v221, v221
	v_pk_add_f32 v[224:225], v[116:117], v[224:225]
	v_mul_f32_e32 v227, v223, v223
	v_fmac_f32_e32 v236, v228, v228
	v_fmac_f32_e32 v237, v226, v226
	v_fmac_f32_e32 v211, v218, v218
	v_fmac_f32_e32 v213, v220, v220
	v_mul_f32_e32 v229, v225, v225
	v_fmac_f32_e32 v238, v210, v210
	v_fmac_f32_e32 v227, v222, v222
	v_add_f32_e32 v210, v236, v237
	v_add_f32_e32 v211, v211, v213
	v_fmac_f32_e32 v239, v212, v212
	v_fmac_f32_e32 v229, v224, v224
	v_add_f32_e32 v210, v210, v238
	v_add_f32_e32 v211, v211, v227
	v_add_f32_e32 v210, v239, v210
	v_add_f32_e32 v211, v229, v211
	v_add_f32_e32 v212, v210, v211
	v_mov_b32_e32 v213, v212
	v_mov_b32_e32 v247, v212
	s_nop 1
	v_permlane16_swap_b32_e32 v247, v213
	v_lshl_add_u64 v[210:211], v[206:207], 1, v[184:185]
	global_store_dwordx4 v[210:211], v[180:183], off
	s_waitcnt lgkmcnt(0)
	s_nop 0
	v_add_f32_e32 v180, v212, v213
	v_mov_b32_e32 v181, v180
	v_mov_b32_e32 v247, v180
	s_nop 1
	v_permlane32_swap_b32_e32 v247, v181
	v_cvt_pk_bf16_f32 v182, v218, v219
	v_cvt_pk_bf16_f32 v183, v220, v221
	v_cvt_pk_bf16_f32 v184, v222, v223
	v_cvt_pk_bf16_f32 v185, v224, v225
	global_store_dwordx4 v[210:211], v[182:185], off offset:256
	s_and_saveexec_b64 s[62:63], s[58:59]
	s_cbranch_execz .LBB0_365
	v_lshlrev_b64 v[182:183], 6, v[208:209]
	v_lshl_add_u64 v[182:183], s[42:43], 0, v[182:183]
	v_lshl_add_u64 v[182:183], s[60:61], 2, v[182:183]
	s_lshl_b32 s70, s87, 2
	v_lshl_add_u64 v[182:183], v[182:183], 0, s[70:71]
	s_waitcnt lgkmcnt(0)
	v_add_f32_e32 v180, v180, v181
	global_store_dword v[182:183], v180, off

; __device__ __forceinline__ unsigned cvt_pk_bf16(float lo, float hi) { unsigned r; asm volatile("v_cvt_pk_bf16_f32 %0, %1, %2" : "=v"(r) : "v"(lo), "v"(hi)); return r; }
;     __device__ __forceinline__ void finish_half(const f32x4 (&acc)[2][2][4][2], const f32x4 (&r)[4][2][2], const Unit& u, int ai, int rl0, int col0, int wc, int fq) const {
;     ...
;         for (int m = 0; m < 4; ++m) { const size_t row = (size_t)(u.pm * BM + rl0 + ai * HALF + m * 16); const size_t off = row * 1024 + col0; float q = 0.f;
; #pragma unroll
;             for (int bj = 0; bj < 2; ++bj) {
;                 const f32x4 v0 = acc[ai][bj][m][0] + r[m][bj][0], v1 = acc[ai][bj][m][1] + r[m][bj][1];
;                 if (out32) { *(f32x4*)(out32 + off + bj * HALF) = v0; *(f32x4*)(out32 + off + bj * HALF + 4) = v1; }
;                 q += (v0[0] * v0[0] + v0[1] * v0[1]) + (v0[2] * v0[2] + v0[3] * v0[3]) + (v1[0] * v1[0] + v1[1] * v1[1]) + (v1[2] * v1[2] + v1[3] * v1[3]);
;                 u32x4 w; w.x = cvt_pk_bf16(v0[0], v0[1]); w.y = cvt_pk_bf16(v0[2], v0[3]); w.z = cvt_pk_bf16(v1[0], v1[1]); w.w = cvt_pk_bf16(v1[2], v1[3]);
;                 *(u32x4*)(hb + off + bj * HALF) = w; }
;     __device__ __forceinline__ void operator()(const f32x4 (&acc)[2][2][4][2], const Unit& u, int wr, int wc, int fr, int fq) const {
;     ...
;                     for (int bj = 0; bj < 2; ++bj) { const size_t off = (size_t)(u.pm * BM + rl0 + ai * HALF + m * 16) * 1024 + col0 + bj * HALF;
;                         r[m][bj][0] = *(const f32x4*)(res32 + off); r[m][bj][1] = *(const f32x4*)(res32 + off + 4); }
.LBB0_371:
	s_or_b64 exec, exec, s[62:63]
	s_waitcnt lgkmcnt(0)
	v_lshlrev_b64 v[130:131], 12, v[208:209]
	v_lshl_add_u64 v[130:131], v[178:179], 0, v[130:131]
	v_add_co_u32_e32 v134, vcc, 0x80000, v130
	s_mov_b64 s[62:63], 0x80000
	s_nop 0
	v_addc_co_u32_e32 v135, vcc, 0, v131, vcc
	v_lshl_add_u64 v[132:133], v[130:131], 0, s[62:63]
	v_lshl_add_u64 v[250:251], v[134:135], 0, v[244:245]
	global_load_dwordx4 v[218:221], v[250:251], off
	v_lshl_add_u64 v[250:251], v[132:133], 0, v[244:245]
	global_load_dwordx4 v[222:225], v[250:251], off offset:16
	v_lshl_add_u64 v[250:251], v[132:133], 0, v[244:245]
	global_load_dwordx4 v[178:181], v[250:251], off offset:528
	v_lshl_add_u64 v[250:251], v[132:133], 0, v[244:245]
	global_load_dwordx4 v[182:185], v[250:251], off offset:512
	v_add_co_u32_e32 v134, vcc, 0x90000, v130
	s_mov_b64 s[62:63], 0x90000
	s_nop 0
	v_addc_co_u32_e32 v135, vcc, 0, v131, vcc
	v_lshl_add_u64 v[132:133], v[130:131], 0, s[62:63]
	v_lshl_add_u64 v[250:251], v[134:135], 0, v[244:245]
	global_load_dwordx4 v[174:177], v[250:251], off
	v_lshl_add_u64 v[250:251], v[132:133], 0, v[244:245]
	global_load_dwordx4 v[170:173], v[250:251], off offset:16
	v_lshl_add_u64 v[250:251], v[132:133], 0, v[244:245]
	global_load_dwordx4 v[162:165], v[250:251], off offset:528
	v_lshl_add_u64 v[250:251], v[132:133], 0, v[244:245]
	global_load_dwordx4 v[166:169], v[250:251], off offset:512
	s_mov_b64 s[62:63], 0xa0000
	v_add_co_u32_e32 v134, vcc, 0xa0000, v130
	v_lshl_add_u64 v[132:133], v[130:131], 0, s[62:63]
	s_nop 0
	v_addc_co_u32_e32 v135, vcc, 0, v131, vcc
	s_mov_b64 s[62:63], 0xb0000
	v_lshl_add_u64 v[138:139], v[130:131], 0, s[62:63]
	v_add_co_u32_e32 v130, vcc, 0xb0000, v130
	v_lshl_add_u64 v[250:251], v[134:135], 0, v[244:245]
	global_load_dwordx4 v[158:161], v[250:251], off
	v_lshl_add_u64 v[250:251], v[132:133], 0, v[244:245]
	global_load_dwordx4 v[154:157], v[250:251], off offset:16
	v_lshl_add_u64 v[250:251], v[132:133], 0, v[244:245]
	global_load_dwordx4 v[142:145], v[250:251], off offset:528
	v_lshl_add_u64 v[250:251], v[132:133], 0, v[244:245]
	global_load_dwordx4 v[146:149], v[250:251], off offset:512
	v_addc_co_u32_e32 v131, vcc, 0, v131, vcc
	v_lshl_add_u64 v[250:251], v[130:131], 0, v[244:245]
	global_load_dwordx4 v[134:137], v[250:251], off
	v_lshl_add_u64 v[250:251], v[138:139], 0, v[244:245]
	global_load_dwordx4 v[150:153], v[250:251], off offset:16
	s_nop 0
	v_lshl_add_u64 v[250:251], v[138:139], 0, v[244:245]
	global_load_dwordx4 v[130:133], v[250:251], off offset:528
	s_nop 0
	v_lshl_add_u64 v[250:251], v[138:139], 0, v[244:245]
	global_load_dwordx4 v[138:141], v[250:251], off offset:512
	v_add_u32_e32 v212, 0x80, v216
	v_add_u32_e32 v210, s51, v212
	v_ashrrev_i32_e32 v211, 31, v210
	s_waitcnt vmcnt(0)
	ds_bpermute_b32 v218, v246, v218
	ds_bpermute_b32 v219, v246, v219
	ds_bpermute_b32 v220, v246, v220
	ds_bpermute_b32 v221, v246, v221
	ds_bpermute_b32 v222, v246, v222
	ds_bpermute_b32 v223, v246, v223
	ds_bpermute_b32 v224, v246, v224
	ds_bpermute_b32 v225, v246, v225
	ds_bpermute_b32 v178, v246, v178
	ds_bpermute_b32 v179, v246, v179
	ds_bpermute_b32 v180, v246, v180
	ds_bpermute_b32 v181, v246, v181
	ds_bpermute_b32 v182, v246, v182
	ds_bpermute_b32 v183, v246, v183
	ds_bpermute_b32 v184, v246, v184
	ds_bpermute_b32 v185, v246, v185
	ds_bpermute_b32 v174, v246, v174
	ds_bpermute_b32 v175, v246, v175
	ds_bpermute_b32 v176, v246, v176
	ds_bpermute_b32 v177, v246, v177
	ds_bpermute_b32 v170, v246, v170
	ds_bpermute_b32 v171, v246, v171
	ds_bpermute_b32 v172, v246, v172
	ds_bpermute_b32 v173, v246, v173
	ds_bpermute_b32 v162, v246, v162
	ds_bpermute_b32 v163, v246, v163
	ds_bpermute_b32 v164, v246, v164
	ds_bpermute_b32 v165, v246, v165
	ds_bpermute_b32 v166, v246, v166
	ds_bpermute_b32 v167, v246, v167
	ds_bpermute_b32 v168, v246, v168
	ds_bpermute_b32 v169, v246, v169
	ds_bpermute_b32 v158, v246, v158
	ds_bpermute_b32 v159, v246, v159
	ds_bpermute_b32 v160, v246, v160
	ds_bpermute_b32 v161, v246, v161
	ds_bpermute_b32 v154, v246, v154
	ds_bpermute_b32 v155, v246, v155
	ds_bpermute_b32 v156, v246, v156
	ds_bpermute_b32 v157, v246, v157
	ds_bpermute_b32 v142, v246, v142
	ds_bpermute_b32 v143, v246, v143
	ds_bpermute_b32 v144, v246, v144
	ds_bpermute_b32 v145, v246, v145
	ds_bpermute_b32 v146, v246, v146
	ds_bpermute_b32 v147, v246, v147
	ds_bpermute_b32 v148, v246, v148
	ds_bpermute_b32 v149, v246, v149
	ds_bpermute_b32 v134, v246, v134
	ds_bpermute_b32 v135, v246, v135
	ds_bpermute_b32 v136, v246, v136
	ds_bpermute_b32 v137, v246, v137
	ds_bpermute_b32 v150, v246, v150
	ds_bpermute_b32 v151, v246, v151
	ds_bpermute_b32 v152, v246, v152
	ds_bpermute_b32 v153, v246, v153
	ds_bpermute_b32 v130, v246, v130
	ds_bpermute_b32 v131, v246, v131
	ds_bpermute_b32 v132, v246, v132
	ds_bpermute_b32 v133, v246, v133
	ds_bpermute_b32 v138, v246, v138
	ds_bpermute_b32 v139, v246, v139
	ds_bpermute_b32 v140, v246, v140
	ds_bpermute_b32 v141, v246, v141
	s_waitcnt lgkmcnt(0)
	v_pk_add_f32 v[220:221], v[64:65], v[220:221]
	v_pk_add_f32 v[218:219], v[62:63], v[218:219]
	v_mul_f32_e32 v226, v221, v221
	v_mul_f32_e32 v213, v219, v219
	s_waitcnt vmcnt(14)
	v_pk_add_f32 v[222:223], v[58:59], v[222:223]
	v_fmac_f32_e32 v213, v218, v218
	v_fmac_f32_e32 v226, v220, v220
	v_add_f32_e32 v213, v213, v226
	v_mul_f32_e32 v226, v223, v223
	v_fmac_f32_e32 v226, v222, v222
	v_cvt_pk_bf16_f32 v218, v218, v219
	v_cvt_pk_bf16_f32 v219, v220, v221
	v_cvt_pk_bf16_f32 v220, v222, v223
	v_lshlrev_b64 v[222:223], 11, v[210:211]
	v_lshl_add_u64 v[222:223], s[40:41], 0, v[222:223]
	v_lshl_add_u64 v[222:223], v[206:207], 1, v[222:223]
	s_waitcnt vmcnt(12)
	v_pk_add_f32 v[184:185], v[56:57], v[184:185]
	v_pk_add_f32 v[182:183], v[54:55], v[182:183]
	v_pk_add_f32 v[224:225], v[60:61], v[224:225]
	v_add_f32_e32 v213, v213, v226
	v_cvt_pk_bf16_f32 v221, v224, v225
	global_store_dwordx4 v[222:223], v[218:221], off
	v_mul_f32_e32 v226, v225, v225
	v_fmac_f32_e32 v226, v224, v224
	v_pk_add_f32 v[218:219], v[52:53], v[180:181]
	v_pk_add_f32 v[180:181], v[50:51], v[178:179]
	v_mul_f32_e32 v178, v183, v183
	v_mul_f32_e32 v179, v185, v185
	v_fmac_f32_e32 v178, v182, v182
	v_fmac_f32_e32 v179, v184, v184
	v_add_f32_e32 v178, v178, v179
	v_mul_f32_e32 v179, v181, v181
	v_fmac_f32_e32 v179, v180, v180
	v_add_f32_e32 v178, v178, v179
	v_mul_f32_e32 v179, v219, v219
	v_fmac_f32_e32 v179, v218, v218
	v_add_f32_e32 v213, v226, v213
	v_add_f32_e32 v178, v179, v178
	v_add_f32_e32 v213, v213, v178
	v_cvt_pk_bf16_f32 v178, v182, v183
	v_cvt_pk_bf16_f32 v179, v184, v185
	v_cvt_pk_bf16_f32 v180, v180, v181
	v_cvt_pk_bf16_f32 v181, v218, v219
	global_store_dwordx4 v[222:223], v[178:181], off offset:256
	s_nop 1
	v_mov_b32_e32 v178, v213
	v_mov_b32_e32 v247, v213
	s_nop 1
	v_permlane16_swap_b32_e32 v247, v178
	s_waitcnt lgkmcnt(0)
	v_add_f32_e32 v178, v213, v178
	v_mov_b32_e32 v179, v178
	v_mov_b32_e32 v247, v178
	s_nop 1
	v_permlane32_swap_b32_e32 v247, v179
	s_and_saveexec_b64 s[62:63], s[58:59]
	s_cbranch_execz .LBB0_373
;     __device__ __forceinline__ void finish_half(const f32x4 (&acc)[2][2][4][2], const f32x4 (&r)[4][2][2], const Unit& u, int ai, int rl0, int col0, int wc, int fq) const {
;     ...
;             q += __shfl_xor(q, 16); q += __shfl_xor(q, 32);
;             if (fq == 0) ssq[row * 16 + u.pn * 4 + wc] = q; }
	v_lshlrev_b64 v[180:181], 6, v[210:211]
	v_lshl_add_u64 v[180:181], s[42:43], 0, v[180:181]
	v_lshl_add_u64 v[180:181], s[60:61], 2, v[180:181]
	s_lshl_b32 s70, s87, 2
	v_lshl_add_u64 v[180:181], v[180:181], 0, s[70:71]
	s_waitcnt lgkmcnt(0)
	v_add_f32_e32 v178, v178, v179
	global_store_dword v[180:181], v178, off
